# speedup vs baseline: 1.0095x; 1.0013x over previous
; #define MFMA(a, b, c) __builtin_amdgcn_mfma_f32_16x16x32_bf16((a), (b), (c), 0, 0, 0)
;     ...
;     for (int kt = 0; kt < nk; ++kt) {
;       if (VAR != 1) { const char* base = lds + scur; bf16x8 a[MI], b[4];
; #pragma unroll
;         for (int i = 0; i < 4; ++i) b[i] = *(const bf16x8*)(base + boff + i * 1024);
; #pragma unroll
;         for (int i = 0; i < MI; ++i) a[i] = *(const bf16x8*)(base + aoff + i * 1024);
; #pragma unroll
;         for (int i = 0; i < MI; ++i)
; #pragma unroll
;           for (int j = 0; j < 4; ++j) acc[i][j] = MFMA(a[i], b[j], acc[i][j]);
;         if (VAR != 2) GLDS(snext)
.LBB0_219:
	s_add_i32 s8, s4, 0
	v_add3_u32 v72, s8, v75, v76
	v_add3_u32 v73, s8, v77, v76
	ds_read_b128 v[80:83], v72
	ds_read_b128 v[84:87], v73 offset:8192
	ds_read_b128 v[88:91], v73 offset:9216
	ds_read_b128 v[92:95], v73 offset:10240
	ds_read_b128 v[96:99], v73 offset:11264
	ds_read_b128 v[228:231], v72 offset:1024
	ds_read_b128 v[232:235], v72 offset:2048
	ds_read_b128 v[100:103], v72 offset:3072
	v_add_u32_e32 v79, s0, v78
	s_nop 0
	v_readfirstlane_b32 s8, v79
	s_waitcnt lgkmcnt(6)
	v_mfma_f32_16x16x32_bf16 v[60:63], v[80:83], v[84:87], v[60:63]
	s_mov_b32 m0, s8
	s_add_i32 s6, s6, 32
	s_cmpk_lg_i32 s6, 0x400
	s_waitcnt lgkmcnt(5)
	v_mfma_f32_16x16x32_bf16 v[56:59], v[80:83], v[88:91], v[56:59]
	s_waitcnt lgkmcnt(4)
	v_mfma_f32_16x16x32_bf16 v[52:55], v[80:83], v[92:95], v[52:55]
	s_waitcnt lgkmcnt(3)
	v_mfma_f32_16x16x32_bf16 v[48:51], v[80:83], v[96:99], v[48:51]
	s_waitcnt lgkmcnt(2)
	v_mfma_f32_16x16x32_bf16 v[44:47], v[228:231], v[84:87], v[44:47]
	v_mfma_f32_16x16x32_bf16 v[40:43], v[228:231], v[88:91], v[40:43]
	v_mfma_f32_16x16x32_bf16 v[36:39], v[228:231], v[92:95], v[36:39]
	v_mfma_f32_16x16x32_bf16 v[32:35], v[228:231], v[96:99], v[32:35]
	v_add_u32_e32 v72, 0x2000, v79
	v_add_u32_e32 v79, 0x4000, v79
	v_readfirstlane_b32 s8, v72
	global_load_lds_dwordx4 v[68:69], off
	s_mov_b32 m0, s8
	v_readfirstlane_b32 s8, v79
	global_load_lds_dwordx4 v[70:71], off
	v_lshl_add_u64 v[72:73], v[70:71], 0, s[50:51]
	s_mov_b32 m0, s8
	s_waitcnt lgkmcnt(1)
	v_mfma_f32_16x16x32_bf16 v[24:27], v[232:235], v[84:87], v[24:27]
	global_load_lds_dwordx4 v[72:73], off
	v_mfma_f32_16x16x32_bf16 v[28:31], v[232:235], v[88:91], v[28:31]
	v_mfma_f32_16x16x32_bf16 v[16:19], v[232:235], v[92:95], v[16:19]
	v_mfma_f32_16x16x32_bf16 v[20:23], v[232:235], v[96:99], v[20:23]
	s_waitcnt lgkmcnt(0)
	v_mfma_f32_16x16x32_bf16 v[8:11], v[100:103], v[84:87], v[8:11]
	v_mfma_f32_16x16x32_bf16 v[12:15], v[100:103], v[88:91], v[12:15]
	v_mfma_f32_16x16x32_bf16 v[0:3], v[100:103], v[92:95], v[0:3]
	v_mfma_f32_16x16x32_bf16 v[4:7], v[100:103], v[96:99], v[4:7]
	s_cbranch_scc0 .LBB0_217
	v_lshl_add_u64 v[68:69], v[68:69], 0, 64
	v_lshl_add_u64 v[70:71], v[70:71], 0, 64
	s_branch .LBB0_218

; #define MFMA(a, b, c) __builtin_amdgcn_mfma_f32_16x16x32_bf16((a), (b), (c), 0, 0, 0)
;     ...
;     for (int kt = 0; kt < nk; ++kt) {
;       if (VAR != 1) { const char* base = lds + scur; bf16x8 a[MI], b[4];
; #pragma unroll
;         for (int i = 0; i < 4; ++i) b[i] = *(const bf16x8*)(base + boff + i * 1024);
; #pragma unroll
;         for (int i = 0; i < MI; ++i) a[i] = *(const bf16x8*)(base + aoff + i * 1024);
; #pragma unroll
;         for (int i = 0; i < MI; ++i)
; #pragma unroll
;           for (int j = 0; j < 4; ++j) acc[i][j] = MFMA(a[i], b[j], acc[i][j]);
;         if (VAR != 2) GLDS(snext)
.LBB0_398:
	s_add_i32 s1, s8, 0
	v_add3_u32 v80, s1, v83, v84
	v_add3_u32 v81, s1, v85, v84
	ds_read_b128 v[72:75], v80
	ds_read_b128 v[76:79], v81 offset:8192
	ds_read_b128 v[88:91], v81 offset:9216
	ds_read_b128 v[92:95], v81 offset:10240
	ds_read_b128 v[96:99], v81 offset:11264
	ds_read_b128 v[228:231], v80 offset:1024
	ds_read_b128 v[232:235], v80 offset:2048
	ds_read_b128 v[100:103], v80 offset:3072
	s_add_i32 s74, s74, 32
	s_cmpk_lg_i32 s74, 0x400
	s_waitcnt lgkmcnt(6)
	v_mfma_f32_16x16x32_bf16 v[60:63], v[72:75], v[76:79], v[60:63]
	s_waitcnt lgkmcnt(5)
	v_mfma_f32_16x16x32_bf16 v[56:59], v[72:75], v[88:91], v[56:59]
	s_waitcnt lgkmcnt(4)
	v_mfma_f32_16x16x32_bf16 v[52:55], v[72:75], v[92:95], v[52:55]
	s_waitcnt lgkmcnt(3)
	v_mfma_f32_16x16x32_bf16 v[48:51], v[72:75], v[96:99], v[48:51]
	s_waitcnt lgkmcnt(2)
	v_mfma_f32_16x16x32_bf16 v[44:47], v[228:231], v[76:79], v[44:47]
	v_mfma_f32_16x16x32_bf16 v[40:43], v[228:231], v[88:91], v[40:43]
	v_mfma_f32_16x16x32_bf16 v[36:39], v[228:231], v[92:95], v[36:39]
	v_mfma_f32_16x16x32_bf16 v[32:35], v[228:231], v[96:99], v[32:35]
	v_add_u32_e32 v80, s9, v86
	s_waitcnt lgkmcnt(1)
	v_mfma_f32_16x16x32_bf16 v[24:27], v[232:235], v[76:79], v[24:27]
	v_readfirstlane_b32 s1, v80
	s_mov_b32 m0, s1
	v_mfma_f32_16x16x32_bf16 v[28:31], v[232:235], v[88:91], v[28:31]
	global_load_lds_dwordx4 v[68:69], off
	v_mfma_f32_16x16x32_bf16 v[16:19], v[232:235], v[92:95], v[16:19]
	v_mfma_f32_16x16x32_bf16 v[20:23], v[232:235], v[96:99], v[20:23]
	v_add_u32_e32 v72, 0x2000, v80
	v_add_u32_e32 v74, 0x4000, v80
	v_readfirstlane_b32 s1, v72
	s_mov_b32 m0, s1
	v_readfirstlane_b32 s1, v74
	global_load_lds_dwordx4 v[70:71], off
	v_lshl_add_u64 v[72:73], v[70:71], 0, s[50:51]
	s_mov_b32 m0, s1
	s_waitcnt lgkmcnt(0)
	v_mfma_f32_16x16x32_bf16 v[8:11], v[100:103], v[76:79], v[8:11]
	global_load_lds_dwordx4 v[72:73], off
	v_mfma_f32_16x16x32_bf16 v[12:15], v[100:103], v[88:91], v[12:15]
	v_mfma_f32_16x16x32_bf16 v[0:3], v[100:103], v[92:95], v[0:3]
	v_mfma_f32_16x16x32_bf16 v[4:7], v[100:103], v[96:99], v[4:7]
	s_cbranch_scc0 .LBB0_396
	v_lshl_add_u64 v[68:69], v[68:69], 0, 64
	v_lshl_add_u64 v[70:71], v[70:71], 0, 64
	s_branch .LBB0_397

; #define MFMA(a, b, c) __builtin_amdgcn_mfma_f32_16x16x32_bf16((a), (b), (c), 0, 0, 0)
;     ...
;     for (int kt = 0; kt < nk; ++kt) {
;       if (VAR != 1) { const char* base = lds + scur; bf16x8 a[MI], b[4];
; #pragma unroll
;         for (int i = 0; i < 4; ++i) b[i] = *(const bf16x8*)(base + boff + i * 1024);
; #pragma unroll
;         for (int i = 0; i < MI; ++i) a[i] = *(const bf16x8*)(base + aoff + i * 1024);
; #pragma unroll
;         for (int i = 0; i < MI; ++i)
; #pragma unroll
;           for (int j = 0; j < 4; ++j) acc[i][j] = MFMA(a[i], b[j], acc[i][j]);
;         if (VAR != 2) GLDS(snext)
.LBB0_749:
	s_add_i32 s1, s62, 0
	v_add3_u32 v92, s1, v107, v108
	v_add3_u32 v88, s1, v109, v108
	ds_read_b128 v[72:75], v92
	ds_read_b128 v[76:79], v88 offset:8192
	ds_read_b128 v[80:83], v88 offset:9216
	ds_read_b128 v[84:87], v88 offset:10240
	ds_read_b128 v[88:91], v88 offset:11264
	ds_read_b128 v[228:231], v92 offset:1024
	ds_read_b128 v[232:235], v92 offset:2048
	ds_read_b128 v[92:95], v92 offset:3072
	v_add_u32_e32 v96, s63, v110
	s_add_i32 s94, s94, 32
	v_readfirstlane_b32 s1, v96
	s_waitcnt lgkmcnt(6)
	v_mfma_f32_16x16x32_bf16 v[60:63], v[72:75], v[76:79], v[60:63]
	s_mov_b32 m0, s1
	s_cmpk_lg_i32 s94, 0x400
	s_waitcnt lgkmcnt(5)
	v_mfma_f32_16x16x32_bf16 v[56:59], v[72:75], v[80:83], v[56:59]
	s_waitcnt lgkmcnt(4)
	v_mfma_f32_16x16x32_bf16 v[52:55], v[72:75], v[84:87], v[52:55]
	s_waitcnt lgkmcnt(3)
	v_mfma_f32_16x16x32_bf16 v[48:51], v[72:75], v[88:91], v[48:51]
	s_waitcnt lgkmcnt(2)
	v_mfma_f32_16x16x32_bf16 v[44:47], v[228:231], v[76:79], v[44:47]
	v_mfma_f32_16x16x32_bf16 v[40:43], v[228:231], v[80:83], v[40:43]
	v_mfma_f32_16x16x32_bf16 v[36:39], v[228:231], v[84:87], v[36:39]
	v_mfma_f32_16x16x32_bf16 v[32:35], v[228:231], v[88:91], v[32:35]
	global_load_lds_dwordx4 v[68:69], off
	s_waitcnt lgkmcnt(1)
	v_mfma_f32_16x16x32_bf16 v[24:27], v[232:235], v[76:79], v[24:27]
	v_mfma_f32_16x16x32_bf16 v[28:31], v[232:235], v[80:83], v[28:31]
	v_mfma_f32_16x16x32_bf16 v[16:19], v[232:235], v[84:87], v[16:19]
	v_mfma_f32_16x16x32_bf16 v[20:23], v[232:235], v[88:91], v[20:23]
	v_add_u32_e32 v72, 0x2000, v96
	v_add_u32_e32 v74, 0x4000, v96
	v_readfirstlane_b32 s1, v72
	s_mov_b32 m0, s1
	v_readfirstlane_b32 s1, v74
	global_load_lds_dwordx4 v[70:71], off
	v_lshl_add_u64 v[72:73], v[70:71], 0, s[50:51]
	s_mov_b32 m0, s1
	s_waitcnt lgkmcnt(0)
	v_mfma_f32_16x16x32_bf16 v[8:11], v[92:95], v[76:79], v[8:11]
	global_load_lds_dwordx4 v[72:73], off
	v_mfma_f32_16x16x32_bf16 v[12:15], v[92:95], v[80:83], v[12:15]
	v_mfma_f32_16x16x32_bf16 v[0:3], v[92:95], v[84:87], v[0:3]
	v_mfma_f32_16x16x32_bf16 v[4:7], v[92:95], v[88:91], v[4:7]
	s_cbranch_scc0 .LBB0_747
	v_lshl_add_u64 v[68:69], v[68:69], 0, 64
	v_lshl_add_u64 v[70:71], v[70:71], 0, 64
	s_branch .LBB0_748

; #define MFMA(a, b, c) __builtin_amdgcn_mfma_f32_16x16x32_bf16((a), (b), (c), 0, 0, 0)
;     ...
;     for (int kt = 0; kt < nk; ++kt) {
;       if (VAR != 1) { const char* base = lds + scur; bf16x8 a[MI], b[4];
; #pragma unroll
;         for (int i = 0; i < 4; ++i) b[i] = *(const bf16x8*)(base + boff + i * 1024);
; #pragma unroll
;         for (int i = 0; i < MI; ++i) a[i] = *(const bf16x8*)(base + aoff + i * 1024);
; #pragma unroll
;         for (int i = 0; i < MI; ++i)
; #pragma unroll
;           for (int j = 0; j < 4; ++j) acc[i][j] = MFMA(a[i], b[j], acc[i][j]);
;         if (VAR != 2) GLDS(snext)
.LBB0_983:
	s_add_i32 s6, s0, 0
	v_add3_u32 v81, s6, v77, v78
	v_add3_u32 v94, s6, v79, v78
	ds_read_b128 v[72:75], v81
	ds_read_b128 v[82:85], v94 offset:8192
	ds_read_b128 v[86:89], v94 offset:9216
	ds_read_b128 v[90:93], v94 offset:10240
	ds_read_b128 v[94:97], v94 offset:11264
	ds_read_b128 v[228:231], v81 offset:1024
	ds_read_b128 v[232:235], v81 offset:2048
	ds_read_b128 v[98:101], v81 offset:3072
	s_add_i32 s4, s4, 32
	s_cmpk_lg_i32 s4, 0x400
	s_waitcnt lgkmcnt(6)
	v_mfma_f32_16x16x32_bf16 v[60:63], v[72:75], v[82:85], v[60:63]
	s_waitcnt lgkmcnt(5)
	v_mfma_f32_16x16x32_bf16 v[56:59], v[72:75], v[86:89], v[56:59]
	s_waitcnt lgkmcnt(4)
	v_mfma_f32_16x16x32_bf16 v[52:55], v[72:75], v[90:93], v[52:55]
	s_waitcnt lgkmcnt(3)
	v_mfma_f32_16x16x32_bf16 v[48:51], v[72:75], v[94:97], v[48:51]
	s_waitcnt lgkmcnt(2)
	v_mfma_f32_16x16x32_bf16 v[44:47], v[228:231], v[82:85], v[44:47]
	v_mfma_f32_16x16x32_bf16 v[40:43], v[228:231], v[86:89], v[40:43]
	v_mfma_f32_16x16x32_bf16 v[36:39], v[228:231], v[90:93], v[36:39]
	v_mfma_f32_16x16x32_bf16 v[32:35], v[228:231], v[94:97], v[32:35]
	v_add_u32_e32 v81, s1, v80
	s_waitcnt lgkmcnt(1)
	v_mfma_f32_16x16x32_bf16 v[28:31], v[232:235], v[82:85], v[28:31]
	v_readfirstlane_b32 s6, v81
	s_mov_b32 m0, s6
	v_mfma_f32_16x16x32_bf16 v[24:27], v[232:235], v[86:89], v[24:27]
	global_load_lds_dwordx4 v[68:69], off
	v_mfma_f32_16x16x32_bf16 v[20:23], v[232:235], v[90:93], v[20:23]
	v_mfma_f32_16x16x32_bf16 v[16:19], v[232:235], v[94:97], v[16:19]
	v_add_u32_e32 v72, 0x2000, v81
	v_add_u32_e32 v74, 0x4000, v81
	v_readfirstlane_b32 s6, v72
	s_mov_b32 m0, s6
	v_readfirstlane_b32 s6, v74
	global_load_lds_dwordx4 v[70:71], off
	v_lshl_add_u64 v[72:73], v[70:71], 0, s[50:51]
	s_mov_b32 m0, s6
	s_waitcnt lgkmcnt(0)
	v_mfma_f32_16x16x32_bf16 v[12:15], v[98:101], v[82:85], v[12:15]
	global_load_lds_dwordx4 v[72:73], off
	v_mfma_f32_16x16x32_bf16 v[8:11], v[98:101], v[86:89], v[8:11]
	v_mfma_f32_16x16x32_bf16 v[4:7], v[98:101], v[90:93], v[4:7]
	v_mfma_f32_16x16x32_bf16 v[0:3], v[98:101], v[94:97], v[0:3]
	s_cbranch_scc0 .LBB0_981
	v_lshl_add_u64 v[68:69], v[68:69], 0, 64
	v_lshl_add_u64 v[70:71], v[70:71], 0, 64
	s_branch .LBB0_982

; #define MFMA(a, b, c) __builtin_amdgcn_mfma_f32_16x16x32_bf16((a), (b), (c), 0, 0, 0)
;     ...
;     for (int kt = 0; kt < nk; ++kt) {
;       if (VAR != 1) { const char* base = lds + scur; bf16x8 a[MI], b[4];
; #pragma unroll
;         for (int i = 0; i < 4; ++i) b[i] = *(const bf16x8*)(base + boff + i * 1024);
; #pragma unroll
;         for (int i = 0; i < MI; ++i) a[i] = *(const bf16x8*)(base + aoff + i * 1024);
; #pragma unroll
;         for (int i = 0; i < MI; ++i)
; #pragma unroll
;           for (int j = 0; j < 4; ++j) acc[i][j] = MFMA(a[i], b[j], acc[i][j]);
;         if (VAR != 2) GLDS(snext)
.LBB0_1314:
	s_add_i32 s1, s4, 0
	v_add3_u32 v81, s1, v77, v78
	v_add3_u32 v94, s1, v79, v78
	ds_read_b128 v[72:75], v81
	ds_read_b128 v[82:85], v94 offset:8192
	ds_read_b128 v[86:89], v94 offset:9216
	ds_read_b128 v[90:93], v94 offset:10240
	ds_read_b128 v[94:97], v94 offset:11264
	ds_read_b128 v[228:231], v81 offset:1024
	ds_read_b128 v[232:235], v81 offset:2048
	ds_read_b128 v[98:101], v81 offset:3072
	s_add_i32 s8, s8, 32
	s_cmpk_lg_i32 s8, 0x400
	s_waitcnt lgkmcnt(6)
	v_mfma_f32_16x16x32_bf16 v[60:63], v[72:75], v[82:85], v[60:63]
	s_waitcnt lgkmcnt(5)
	v_mfma_f32_16x16x32_bf16 v[56:59], v[72:75], v[86:89], v[56:59]
	s_waitcnt lgkmcnt(4)
	v_mfma_f32_16x16x32_bf16 v[52:55], v[72:75], v[90:93], v[52:55]
	s_waitcnt lgkmcnt(3)
	v_mfma_f32_16x16x32_bf16 v[48:51], v[72:75], v[94:97], v[48:51]
	s_waitcnt lgkmcnt(2)
	v_mfma_f32_16x16x32_bf16 v[44:47], v[228:231], v[82:85], v[44:47]
	v_mfma_f32_16x16x32_bf16 v[40:43], v[228:231], v[86:89], v[40:43]
	v_mfma_f32_16x16x32_bf16 v[36:39], v[228:231], v[90:93], v[36:39]
	v_mfma_f32_16x16x32_bf16 v[32:35], v[228:231], v[94:97], v[32:35]
	v_add_u32_e32 v81, s5, v80
	s_waitcnt lgkmcnt(1)
	v_mfma_f32_16x16x32_bf16 v[28:31], v[232:235], v[82:85], v[28:31]
	v_readfirstlane_b32 s1, v81
	s_mov_b32 m0, s1
	v_mfma_f32_16x16x32_bf16 v[24:27], v[232:235], v[86:89], v[24:27]
	global_load_lds_dwordx4 v[68:69], off
	v_mfma_f32_16x16x32_bf16 v[20:23], v[232:235], v[90:93], v[20:23]
	v_mfma_f32_16x16x32_bf16 v[16:19], v[232:235], v[94:97], v[16:19]
	v_add_u32_e32 v72, 0x2000, v81
	v_add_u32_e32 v74, 0x4000, v81
	v_readfirstlane_b32 s1, v72
	s_mov_b32 m0, s1
	v_readfirstlane_b32 s1, v74
	global_load_lds_dwordx4 v[70:71], off
	v_lshl_add_u64 v[72:73], v[70:71], 0, s[50:51]
	s_mov_b32 m0, s1
	s_waitcnt lgkmcnt(0)
	v_mfma_f32_16x16x32_bf16 v[12:15], v[98:101], v[82:85], v[12:15]
	global_load_lds_dwordx4 v[72:73], off
	v_mfma_f32_16x16x32_bf16 v[8:11], v[98:101], v[86:89], v[8:11]
	v_mfma_f32_16x16x32_bf16 v[4:7], v[98:101], v[90:93], v[4:7]
	v_mfma_f32_16x16x32_bf16 v[0:3], v[98:101], v[94:97], v[0:3]
	s_cbranch_scc0 .LBB0_1312
	v_lshl_add_u64 v[68:69], v[68:69], 0, 64
	v_lshl_add_u64 v[70:71], v[70:71], 0, 64
	s_branch .LBB0_1313
